# C-unit tile loop rewritten by hand: triple-buffered LDS, 1 barrier/tile, QK-softmax-PV software pipelined
# speedup vs baseline: 1.0091x; 1.0091x over previous
; template <int MODE>
; DI void attn_unit(unsigned char* lds, const AttnParams& ap, int b, int h, int qb, int tid) {
;     ...
;   const int qpos = qb * 256 + wave * 32 + r32, cw = qb * 4 + (wave >> 1);
;   bf16x8 qf[4];
;   { const bf16_t* qp = ap.P + (tokb + qpos) * PLD + qcol0 + h * 64 + 8 * hi;
; #pragma unroll
;     for (int ks = 0; ks < 4; ++ks) qf[ks] = *(const bf16x8*)(qp + 16 * ks); }
;   bf16_t* Ks0 = (bf16_t*)lds; bf16_t* Vs0 = Ks0 + NCH * 64 * 72; volatile int* flags = (volatile int*)(lds + 2 * NCH * 64 * 72 * 2);
;   const int jhi = 4 * qb + 3, jlo = (MODE == 0) ? ((4 * qb - 8 > 0) ? 4 * qb - 8 : 0) : 0, ntiles = jhi - jlo + 1;
;   const int lrow = tid >> 3, lch = tid & 7;
;   const bf16_t* kg = ap.P + (tokb + lrow) * PLD + kcol0 + h * 64 + 8 * lch;
;   const bf16_t* vg = Vt + (size_t)bh * 256 * 4096 + lrow * 64 + 8 * lch;
;   const int j0 = (MODE == 2) ? jhi : jlo;
;   u32x4 kreg[NCH], vreg[NCH];
; #pragma unroll
;   for (int c = 0; c < NCH; ++c) { const int jc = (MODE == 2) ? j0 - c : j0 + c; kreg[c] = *(const u32x4*)(kg + (size_t)jc * 64 * PLD); vreg[c] = *(const u32x4*)(vg + (size_t)jc * 4096); }
;   f32x16 O0[2], O1[2]; float l0 = 0.f, l1 = 0.f, cum = 0.f;
; #pragma unroll
;   for (int eb = 0; eb < 2; ++eb) { O0[eb] = splat16(0.f); O1[eb] = splat16(0.f); }
;   bool wdone = false;
;   if (MODE == 2 && D_EARLY) { if (tid < 8) flags[tid] = 0; }
;   for (int n = 0; n < ntiles; n += NCH) {
;     const int jb = (MODE == 2) ? jhi - n : jlo + n;
;     __syncthreads();
;     if (MODE == 2 && D_EARLY) { int alld = 1;
; #pragma unroll
;       for (int w = 0; w < 8; ++w) alld &= flags[w];
;       if (alld) break; }
; #pragma unroll
;     for (int c = 0; c < NCH; ++c) { *(u32x4*)(Ks0 + (c * 64 + lrow) * 72 + 8 * lch) = kreg[c]; *(u32x4*)(Vs0 + (c * 64 + lrow) * 72 + 8 * lch) = vreg[c]; }
;     __syncthreads();
;     if (n + NCH < ntiles) {
; #pragma unroll
;       for (int c = 0; c < NCH; ++c) { const int jn = (MODE == 2) ? jb - NCH - c : jb + NCH + c; kreg[c] = *(const u32x4*)(kg + (size_t)jn * 64 * PLD); vreg[c] = *(const u32x4*)(vg + (size_t)jn * 4096); } }
; #pragma unroll
;     for (int c = 0; c < NCH; ++c) {
;     const int j = (MODE == 2) ? jb - c : jb + c;
;     const bf16_t* Ks = Ks0 + c * 64 * 72; const bf16_t* Vs = Vs0 + c * 64 * 72;
;     const bool active = (j <= cw) && (MODE != 0 || j >= cw - 8);
;     if (!active) continue;
.LBB0_845:
	v_readlane_b32 s0, v255, 51
	v_readlane_b32 s1, v255, 52
	s_andn2_saveexec_b64 s[6:7], s[0:1]
	s_cbranch_execz .LBB0_853
	v_mov_b32_e32 v1, v156
	v_readlane_b32 s0, v255, 25
	v_ashrrev_i32_e32 v2, 1, v1
	v_and_b32_e32 v2, 0xffffffe0, v2
	v_and_b32_e32 v7, 31, v1
	v_lshl_add_u32 v2, v0, 8, v2
	v_or_b32_e32 v2, v2, v7
	v_lshlrev_b32_e32 v32, 14, v4
	v_ashrrev_i32_e32 v3, 31, v2
	v_readlane_b32 s1, v255, 26
	v_lshl_add_u64 v[134:135], v[2:3], 0, v[32:33]
	v_bfe_u32 v47, v1, 5, 1
	v_mov_b64_e32 v[2:3], s[0:1]
	v_mad_u64_u32 v[8:9], s[0:1], v134, s82, v[2:3]
	v_mad_i32_i24 v9, v135, s82, v9
	v_lshlrev_b32_e32 v10, 7, v5
	v_mov_b32_e32 v11, v33
	v_lshl_add_u64 v[8:9], v[8:9], 0, v[10:11]
	v_lshlrev_b32_e32 v132, 4, v47
	v_mov_b32_e32 v133, v33
	v_lshl_add_u64 v[8:9], v[8:9], 0, v[132:133]
	v_ashrrev_i32_e32 v14, 3, v1
	global_load_dwordx4 v[112:115], v[8:9], off offset:3584
	global_load_dwordx4 v[42:45], v[8:9], off offset:3616
	global_load_dwordx4 v[38:41], v[8:9], off offset:3648
	global_load_dwordx4 v[34:37], v[8:9], off offset:3680
	v_add_u32_e32 v8, v14, v32
	v_mad_i64_i32 v[2:3], s[0:1], v8, s82, v[2:3]
	v_lshlrev_b32_e32 v8, 4, v1
	v_and_b32_e32 v32, 0x70, v8
	v_lshlrev_b32_e32 v8, 21, v5
	v_readlane_b32 s0, v255, 41
	v_lshl_add_u64 v[2:3], v[2:3], 0, v[10:11]
	v_lshl_or_b32 v8, v4, 23, v8
	v_mov_b32_e32 v9, v33
	v_readlane_b32 s1, v255, 42
	v_lshlrev_b32_e32 v12, 6, v14
	v_lshl_add_u64 v[2:3], v[2:3], 0, v[32:33]
	v_lshl_add_u64 v[10:11], s[0:1], 0, v[8:9]
	v_ashrrev_i32_e32 v13, 31, v12
	s_movk_i32 s0, 0x1000
	v_lshlrev_b64 v[12:13], 1, v[12:13]
	v_add_co_u32_e32 v2, vcc, s0, v2
	v_lshl_add_u64 v[10:11], v[10:11], 0, v[12:13]
	s_nop 0
	v_addc_co_u32_e32 v3, vcc, 0, v3, vcc
	v_lshl_add_u64 v[10:11], v[10:11], 0, v[32:33]
	global_load_dwordx4 v[120:123], v[2:3], off
	global_load_dwordx4 v[116:119], v[10:11], off
	v_ashrrev_i32_e32 v157, 7, v1
	v_lshlrev_b32_e32 v0, 2, v0
	v_mul_lo_u32 v1, v14, s68
	v_or_b32_e32 v12, v12, v32
	v_readlane_b32 s0, v255, 47
	v_add_u32_e32 v191, v157, v0
	v_add3_u32 v190, 0, v32, v1
	v_or_b32_e32 v192, 3, v0
	v_lshl_add_u64 v[0:1], v[12:13], 0, v[8:9]
	v_readlane_b32 s1, v255, 48
	v_add_u16_e32 v2, -1, v6
	v_and_b32_e32 v2, 3, v2
	v_lshl_add_u64 v[136:137], s[0:1], 0, v[0:1]
	v_mad_i64_i32 v[0:1], s[0:1], v14, s82, 0
	s_mov_b32 s0, 0x6880000
	s_nop 0
	v_mad_u64_u32 v[0:1], s[0:1], v4, s0, v[0:1]
	v_lshlrev_b32_e32 v2, 7, v2
	v_mov_b32_e32 v3, v33
	v_lshl_add_u64 v[0:1], v[0:1], 0, v[2:3]
	v_readlane_b32 s0, v255, 49
	v_lshl_add_u64 v[0:1], v[0:1], 0, v[32:33]
	v_readlane_b32 s1, v255, 50
	v_mov_b32_e32 v14, v33
	v_mov_b32_e32 v15, v33
	v_lshlrev_b32_e32 v46, 6, v5
	v_mul_u32_u24_e32 v155, 0x90, v7
	v_lshl_add_u64 v[138:139], s[0:1], 0, v[0:1]
	v_mov_b32_e32 v32, v33
	v_mov_b32_e32 v0, v33
	v_mov_b32_e32 v1, v33
	v_mov_b32_e32 v2, v33
	v_mov_b32_e32 v4, v33
	v_mov_b32_e32 v5, v33
	v_mov_b32_e32 v6, v33
	v_mov_b32_e32 v7, v33
	v_mov_b32_e32 v8, v33
	v_mov_b32_e32 v10, v33
	v_mov_b32_e32 v11, v33
	v_mov_b32_e32 v12, v33
	v_mov_b32_e32 v13, v33
	v_mov_b64_e32 v[78:79], v[14:15]
	v_mov_b64_e32 v[30:31], v[14:15]
	v_mov_b64_e32 v[94:95], v[14:15]
	s_mov_b32 s4, 0
	v_add_u32_e32 v133, 0, v132
	s_mov_b64 s[0:1], 0
	v_mov_b64_e32 v[76:77], v[12:13]
	v_mov_b64_e32 v[74:75], v[10:11]
	v_mov_b64_e32 v[72:73], v[8:9]
	v_mov_b64_e32 v[70:71], v[6:7]
	v_mov_b64_e32 v[68:69], v[4:5]
	v_mov_b64_e32 v[66:67], v[2:3]
	v_mov_b64_e32 v[64:65], v[0:1]
	v_mov_b64_e32 v[28:29], v[12:13]
	v_mov_b64_e32 v[26:27], v[10:11]
	v_mov_b64_e32 v[24:25], v[8:9]
	v_mov_b64_e32 v[22:23], v[6:7]
	v_mov_b64_e32 v[20:21], v[4:5]
	v_mov_b64_e32 v[18:19], v[2:3]
	v_mov_b64_e32 v[16:17], v[0:1]
	v_mov_b64_e32 v[92:93], v[12:13]
	v_mov_b64_e32 v[90:91], v[10:11]
	v_mov_b64_e32 v[88:89], v[8:9]
	v_mov_b64_e32 v[86:87], v[6:7]
	v_mov_b64_e32 v[84:85], v[4:5]
	v_mov_b64_e32 v[82:83], v[2:3]
	v_mov_b64_e32 v[80:81], v[0:1]
	v_mov_b64_e32 v[140:141], v[32:33]
	v_readfirstlane_b32 s5, v191
	v_readfirstlane_b32 s8, v192
	s_mov_b64 s[2:3], 0x68800
	global_load_dwordx4 v[96:99], v[138:139], off
	global_load_dwordx4 v[100:103], v[136:137], off
	v_lshl_add_u64 v[138:139], v[138:139], 0, s[2:3]
	v_lshl_add_u64 v[136:137], v[136:137], 0, s[18:19]
	v_add_u32_e32 v133, v133, v155
	s_mov_b32 s9, 0
	s_movk_i32 s10, 0x4800
	s_mov_b32 s11, 0x9000
	s_waitcnt vmcnt(2)
	ds_write_b128 v190, v[120:123]
	ds_write_b128 v190, v[116:119] offset:9216
	s_waitcnt vmcnt(0)
	ds_write_b128 v190, v[96:99] offset:18432
	ds_write_b128 v190, v[100:103] offset:27648
	v_mov_b32_e32 v32, v133
	v_add_u32_e32 v157, s10, v133
	v_add_u32_e32 v146, s11, v190
	s_waitcnt lgkmcnt(0)
	s_barrier
	ds_read_b128 v[166:169], v32
	ds_read_b128 v[170:173], v32 offset:32
	v_mov_b32_e32 v158, 0
	v_mov_b32_e32 v159, 0
	v_mov_b32_e32 v160, 0
	v_mov_b32_e32 v161, 0
	v_mov_b32_e32 v162, 0
	v_mov_b32_e32 v163, 0
	v_mov_b32_e32 v164, 0
	v_mov_b32_e32 v165, 0
	v_mov_b32_e32 v150, 0
	v_mov_b32_e32 v151, 0
	s_mov_b32 s4, 0
	s_waitcnt lgkmcnt(0)
	v_mfma_f32_32x32x16_bf16 v[96:111], v[166:169], v[112:115], v[48:63]
	v_mfma_f32_32x32x16_bf16 v[96:111], v[170:173], v[42:45], v[96:111]
	ds_read_b128 v[166:169], v32 offset:64
	ds_read_b128 v[170:173], v32 offset:96
	v_mov_b32_e32 v174, 0
	v_mov_b32_e32 v175, 0
	v_mov_b32_e32 v176, 0
	v_mov_b32_e32 v177, 0
	v_mov_b32_e32 v178, 0
	v_mov_b32_e32 v179, 0
	v_mov_b32_e32 v180, 0
	v_mov_b32_e32 v181, 0
	v_mov_b32_e32 v182, 0
	v_mov_b32_e32 v183, 0
	v_mov_b32_e32 v184, 0
	v_mov_b32_e32 v185, 0
	v_mov_b32_e32 v186, 0
	v_mov_b32_e32 v187, 0
	v_mov_b32_e32 v188, 0
	v_mov_b32_e32 v189, 0
; DI float ex2(float x) { return __builtin_amdgcn_exp2f(x); }
; #define MFMA32(a, b, c) __builtin_amdgcn_mfma_f32_32x32x16_bf16((a), (b), (c), 0, 0, 0)
; template <int MODE>
; DI void attn_unit(unsigned char* lds, const AttnParams& ap, int b, int h, int qb, int tid) {
;     ...
;     if (MODE == 1) {
; #pragma unroll
;       for (int kh = 0; kh < 2; ++kh) {
;         const bf16_t* kb = Ks + (32 * kh + r32) * 72 + 8 * hi;
;         bf16x8 p0[2], p1[2];
;         { f32x16 s0 = splat16(ap.negM);
;           s0 = MFMA32(*(const bf16x8*)(kb), qf[0], s0); s0 = MFMA32(*(const bf16x8*)(kb + 16), qf[1], s0);
; #pragma unroll
;           for (int i = 0; i < 16; ++i) { s0[i] = ex2(s0[i]); l0 += s0[i]; }
;           p0[0] = pack8(s0, 0); p0[1] = pack8(s0, 1); }
;         { f32x16 s1 = splat16(ap.negM);
;           s1 = MFMA32(*(const bf16x8*)(kb + 32), qf[2], s1); s1 = MFMA32(*(const bf16x8*)(kb + 48), qf[3], s1);
; #pragma unroll
;           for (int i = 0; i < 16; ++i) { s1[i] = ex2(s1[i]); l1 += s1[i]; }
;           p1[0] = pack8(s1, 0); p1[1] = pack8(s1, 1); }
; #pragma unroll
;         for (int kk = 0; kk < 2; ++kk) {
; #pragma unroll
;           for (int eb = 0; eb < 2; ++eb) { const bf16_t* vb = Vs + (32 * eb + r32) * 72 + 32 * kh + 16 * kk + 8 * hi; const bf16x8 vf = *(const bf16x8*)vb;
;             O0[eb] = MFMA32(vf, p0[kk], O0[eb]); O1[eb] = MFMA32(vf, p1[kk], O1[eb]); } }
.Lc_tile_loop:
	global_load_dwordx4 v[204:207], v[138:139], off
	global_load_dwordx4 v[142:145], v[136:137], off
	v_lshl_add_u64 v[138:139], v[138:139], 0, s[2:3]
	v_lshl_add_u64 v[136:137], v[136:137], 0, s[18:19]
	s_waitcnt lgkmcnt(0)
	v_mfma_f32_32x32x16_bf16 v[116:131], v[166:169], v[38:41], v[48:63]
	v_exp_f32_e32 v96, v96
	v_exp_f32_e32 v97, v97
	v_exp_f32_e32 v98, v98
	v_exp_f32_e32 v99, v99
	v_mfma_f32_32x32x16_bf16 v[116:131], v[170:173], v[34:37], v[116:131]
	v_exp_f32_e32 v100, v100
	v_exp_f32_e32 v101, v101
	v_exp_f32_e32 v102, v102
	v_exp_f32_e32 v103, v103
	ds_read_b128 v[166:169], v32 offset:4608
	ds_read_b128 v[170:173], v32 offset:4640
	v_mfma_f32_32x32x16_bf16 v[80:95], v[174:177], v[158:161], v[80:95]
	v_exp_f32_e32 v104, v104
	v_exp_f32_e32 v105, v105
	v_add_f32_e32 v141, v141, v96
	v_add_f32_e32 v150, v150, v97
	v_add_f32_e32 v141, v141, v98
	v_add_f32_e32 v150, v150, v99
	v_mfma_f32_32x32x16_bf16 v[16:31], v[182:185], v[158:161], v[16:31]
	v_exp_f32_e32 v106, v106
	v_exp_f32_e32 v107, v107
	v_cvt_pk_bf16_f32 v158, v96, v97
	v_cvt_pk_bf16_f32 v159, v98, v99
	v_add_f32_e32 v141, v141, v100
	v_add_f32_e32 v150, v150, v101
	v_mfma_f32_32x32x16_bf16 v[80:95], v[178:181], v[162:165], v[80:95]
	v_exp_f32_e32 v108, v108
	v_exp_f32_e32 v109, v109
	v_cvt_pk_bf16_f32 v160, v100, v101
	v_cvt_pk_bf16_f32 v161, v102, v103
	v_add_f32_e32 v141, v141, v102
	v_add_f32_e32 v150, v150, v103
	v_mfma_f32_32x32x16_bf16 v[16:31], v[186:189], v[162:165], v[16:31]
	ds_read_b128 v[174:177], v32 offset:9216
	ds_read_b128 v[178:181], v32 offset:9248
	ds_read_b128 v[182:185], v32 offset:13824
	ds_read_b128 v[186:189], v32 offset:13856
	v_exp_f32_e32 v110, v110
	v_exp_f32_e32 v111, v111
	v_add_f32_e32 v141, v141, v104
	v_add_f32_e32 v150, v150, v105
	v_add_f32_e32 v141, v141, v106
	v_add_f32_e32 v150, v150, v107
	v_add_f32_e32 v141, v141, v108
	v_add_f32_e32 v150, v150, v109
	v_cvt_pk_bf16_f32 v162, v104, v105
	v_cvt_pk_bf16_f32 v163, v106, v107
	v_cvt_pk_bf16_f32 v164, v108, v109
	v_add_f32_e32 v141, v141, v110
	v_add_f32_e32 v150, v150, v111
	v_cvt_pk_bf16_f32 v165, v110, v111
	s_waitcnt lgkmcnt(0)
	v_mfma_f32_32x32x16_bf16 v[96:111], v[166:169], v[112:115], v[48:63]
	v_exp_f32_e32 v116, v116
	v_exp_f32_e32 v117, v117
	v_exp_f32_e32 v118, v118
	v_exp_f32_e32 v119, v119
	v_mfma_f32_32x32x16_bf16 v[96:111], v[170:173], v[42:45], v[96:111]
	v_exp_f32_e32 v120, v120
	v_exp_f32_e32 v121, v121
	v_exp_f32_e32 v122, v122
	v_exp_f32_e32 v123, v123
	ds_read_b128 v[166:169], v32 offset:4672
	ds_read_b128 v[170:173], v32 offset:4704
	v_mfma_f32_32x32x16_bf16 v[64:79], v[174:177], v[158:161], v[64:79]
	v_exp_f32_e32 v124, v124
	v_exp_f32_e32 v125, v125
	v_add_f32_e32 v140, v140, v116
	v_add_f32_e32 v151, v151, v117
	v_add_f32_e32 v140, v140, v118
	v_add_f32_e32 v151, v151, v119
	v_mfma_f32_32x32x16_bf16 v[0:15], v[182:185], v[158:161], v[0:15]
	v_exp_f32_e32 v126, v126
	v_exp_f32_e32 v127, v127
	v_cvt_pk_bf16_f32 v158, v116, v117
	v_cvt_pk_bf16_f32 v159, v118, v119
	v_add_f32_e32 v140, v140, v120
	v_add_f32_e32 v151, v151, v121
	v_mfma_f32_32x32x16_bf16 v[64:79], v[178:181], v[162:165], v[64:79]
	v_exp_f32_e32 v128, v128
	v_exp_f32_e32 v129, v129
	v_cvt_pk_bf16_f32 v160, v120, v121
	v_cvt_pk_bf16_f32 v161, v122, v123
	v_add_f32_e32 v140, v140, v122
	v_add_f32_e32 v151, v151, v123
	v_mfma_f32_32x32x16_bf16 v[0:15], v[186:189], v[162:165], v[0:15]
	v_exp_f32_e32 v130, v130
	v_exp_f32_e32 v131, v131
	v_add_f32_e32 v140, v140, v124
	v_add_f32_e32 v151, v151, v125
	v_add_f32_e32 v140, v140, v126
	v_add_f32_e32 v151, v151, v127
	v_add_f32_e32 v140, v140, v128
	v_add_f32_e32 v151, v151, v129
	v_cvt_pk_bf16_f32 v162, v124, v125
	v_cvt_pk_bf16_f32 v163, v126, v127
	v_cvt_pk_bf16_f32 v164, v128, v129
	v_add_f32_e32 v140, v140, v130
	v_add_f32_e32 v151, v151, v131
	v_cvt_pk_bf16_f32 v165, v130, v131
	s_waitcnt lgkmcnt(0)
; DI float ex2(float x) { return __builtin_amdgcn_exp2f(x); }
; template <int MODE>
; DI void attn_unit(unsigned char* lds, const AttnParams& ap, int b, int h, int qb, int tid) {
;     ...
;   for (int n = 0; n < ntiles; n += NCH) {
;     const int jb = (MODE == 2) ? jhi - n : jlo + n;
;     __syncthreads();
;     if (MODE == 2 && D_EARLY) { int alld = 1;
; #pragma unroll
;       for (int w = 0; w < 8; ++w) alld &= flags[w];
;       if (alld) break; }
; #pragma unroll
;     for (int c = 0; c < NCH; ++c) { *(u32x4*)(Ks0 + (c * 64 + lrow) * 72 + 8 * lch) = kreg[c]; *(u32x4*)(Vs0 + (c * 64 + lrow) * 72 + 8 * lch) = vreg[c]; }
;     __syncthreads();
;     if (n + NCH < ntiles) {
; #pragma unroll
;       for (int c = 0; c < NCH; ++c) { const int jn = (MODE == 2) ? jb - NCH - c : jb + NCH + c; kreg[c] = *(const u32x4*)(kg + (size_t)jn * 64 * PLD); vreg[c] = *(const u32x4*)(vg + (size_t)jn * 4096); } }
; #pragma unroll
;     for (int c = 0; c < NCH; ++c) {
;     const int j = (MODE == 2) ? jb - c : jb + c;
;     const bf16_t* Ks = Ks0 + c * 64 * 72; const bf16_t* Vs = Vs0 + c * 64 * 72;
;     const bool active = (j <= cw) && (MODE != 0 || j >= cw - 8);
;     if (!active) continue;
;     if (MODE == 2 && D_EARLY && wdone) continue;
;     if (MODE == 1) {
; #pragma unroll
;       for (int kh = 0; kh < 2; ++kh) {
;         const bf16_t* kb = Ks + (32 * kh + r32) * 72 + 8 * hi;
;         bf16x8 p0[2], p1[2];
;         { f32x16 s0 = splat16(ap.negM);
;           s0 = MFMA32(*(const bf16x8*)(kb), qf[0], s0); s0 = MFMA32(*(const bf16x8*)(kb + 16), qf[1], s0);
; #pragma unroll
;           for (int i = 0; i < 16; ++i) { s0[i] = ex2(s0[i]); l0 += s0[i]; }
;           p0[0] = pack8(s0, 0); p0[1] = pack8(s0, 1); }
;         { f32x16 s1 = splat16(ap.negM);
;           s1 = MFMA32(*(const bf16x8*)(kb + 32), qf[2], s1); s1 = MFMA32(*(const bf16x8*)(kb + 48), qf[3], s1);
; #pragma unroll
;           for (int i = 0; i < 16; ++i) { s1[i] = ex2(s1[i]); l1 += s1[i]; }
;           p1[0] = pack8(s1, 0); p1[1] = pack8(s1, 1); }
; #pragma unroll
;         for (int kk = 0; kk < 2; ++kk) {
; #pragma unroll
;           for (int eb = 0; eb < 2; ++eb) { const bf16_t* vb = Vs + (32 * eb + r32) * 72 + 32 * kh + 16 * kk + 8 * hi; const bf16x8 vf = *(const bf16x8*)vb;
;             O0[eb] = MFMA32(vf, p0[kk], O0[eb]); O1[eb] = MFMA32(vf, p1[kk], O1[eb]); } }
;       }
	v_mfma_f32_32x32x16_bf16 v[116:131], v[166:169], v[38:41], v[48:63]
	v_exp_f32_e32 v96, v96
	v_exp_f32_e32 v97, v97
	v_exp_f32_e32 v98, v98
	v_exp_f32_e32 v99, v99
	v_mfma_f32_32x32x16_bf16 v[116:131], v[170:173], v[34:37], v[116:131]
	v_exp_f32_e32 v100, v100
	v_exp_f32_e32 v101, v101
	v_exp_f32_e32 v102, v102
	v_exp_f32_e32 v103, v103
	ds_read_b128 v[166:169], v157
	ds_read_b128 v[170:173], v157 offset:32
	v_mfma_f32_32x32x16_bf16 v[80:95], v[174:177], v[158:161], v[80:95]
	v_exp_f32_e32 v104, v104
	v_exp_f32_e32 v105, v105
	v_add_f32_e32 v141, v141, v96
	v_add_f32_e32 v150, v150, v97
	v_add_f32_e32 v141, v141, v98
	v_add_f32_e32 v150, v150, v99
	v_mfma_f32_32x32x16_bf16 v[16:31], v[182:185], v[158:161], v[16:31]
	v_exp_f32_e32 v106, v106
	v_exp_f32_e32 v107, v107
	v_cvt_pk_bf16_f32 v158, v96, v97
	v_cvt_pk_bf16_f32 v159, v98, v99
	v_add_f32_e32 v141, v141, v100
	v_add_f32_e32 v150, v150, v101
	v_mfma_f32_32x32x16_bf16 v[80:95], v[178:181], v[162:165], v[80:95]
	v_exp_f32_e32 v108, v108
	v_exp_f32_e32 v109, v109
	v_cvt_pk_bf16_f32 v160, v100, v101
	v_cvt_pk_bf16_f32 v161, v102, v103
	v_add_f32_e32 v141, v141, v102
	v_add_f32_e32 v150, v150, v103
	v_mfma_f32_32x32x16_bf16 v[16:31], v[186:189], v[162:165], v[16:31]
	ds_read_b128 v[174:177], v32 offset:9280
	ds_read_b128 v[178:181], v32 offset:9312
	ds_read_b128 v[182:185], v32 offset:13888
	ds_read_b128 v[186:189], v32 offset:13920
	v_exp_f32_e32 v110, v110
	v_exp_f32_e32 v111, v111
	v_add_f32_e32 v141, v141, v104
	v_add_f32_e32 v150, v150, v105
	v_add_f32_e32 v141, v141, v106
	v_add_f32_e32 v150, v150, v107
	v_add_f32_e32 v141, v141, v108
	v_add_f32_e32 v150, v150, v109
	v_cvt_pk_bf16_f32 v162, v104, v105
	v_cvt_pk_bf16_f32 v163, v106, v107
	v_cvt_pk_bf16_f32 v164, v108, v109
	v_add_f32_e32 v141, v141, v110
	v_add_f32_e32 v150, v150, v111
	v_cvt_pk_bf16_f32 v165, v110, v111
	s_waitcnt lgkmcnt(0)
	v_mfma_f32_32x32x16_bf16 v[96:111], v[166:169], v[112:115], v[48:63]
	v_exp_f32_e32 v116, v116
	v_exp_f32_e32 v117, v117
	v_exp_f32_e32 v118, v118
	v_exp_f32_e32 v119, v119
	v_mfma_f32_32x32x16_bf16 v[96:111], v[170:173], v[42:45], v[96:111]
	v_exp_f32_e32 v120, v120
	v_exp_f32_e32 v121, v121
	v_exp_f32_e32 v122, v122
	v_exp_f32_e32 v123, v123
	ds_read_b128 v[166:169], v157 offset:64
	ds_read_b128 v[170:173], v157 offset:96
	v_mfma_f32_32x32x16_bf16 v[64:79], v[174:177], v[158:161], v[64:79]
	v_exp_f32_e32 v124, v124
	v_exp_f32_e32 v125, v125
	v_add_f32_e32 v140, v140, v116
	v_add_f32_e32 v151, v151, v117
	v_add_f32_e32 v140, v140, v118
	v_add_f32_e32 v151, v151, v119
	v_mfma_f32_32x32x16_bf16 v[0:15], v[182:185], v[158:161], v[0:15]
	v_exp_f32_e32 v126, v126
	v_exp_f32_e32 v127, v127
	v_cvt_pk_bf16_f32 v158, v116, v117
	v_cvt_pk_bf16_f32 v159, v118, v119
	v_add_f32_e32 v140, v140, v120
	v_add_f32_e32 v151, v151, v121
	v_mfma_f32_32x32x16_bf16 v[64:79], v[178:181], v[162:165], v[64:79]
	v_exp_f32_e32 v128, v128
	v_exp_f32_e32 v129, v129
	v_cvt_pk_bf16_f32 v160, v120, v121
	v_cvt_pk_bf16_f32 v161, v122, v123
	v_add_f32_e32 v140, v140, v122
	v_add_f32_e32 v151, v151, v123
	v_mfma_f32_32x32x16_bf16 v[0:15], v[186:189], v[162:165], v[0:15]
	v_exp_f32_e32 v130, v130
	v_exp_f32_e32 v131, v131
	v_add_f32_e32 v140, v140, v124
	v_add_f32_e32 v151, v151, v125
	v_add_f32_e32 v140, v140, v126
	v_add_f32_e32 v151, v151, v127
	v_add_f32_e32 v140, v140, v128
	v_add_f32_e32 v151, v151, v129
	v_cvt_pk_bf16_f32 v162, v124, v125
	v_cvt_pk_bf16_f32 v163, v126, v127
	v_cvt_pk_bf16_f32 v164, v128, v129
	v_add_f32_e32 v140, v140, v130
	v_add_f32_e32 v151, v151, v131
	v_cvt_pk_bf16_f32 v165, v130, v131
	s_waitcnt vmcnt(0)
	ds_write_b128 v146, v[204:207]
	ds_write_b128 v146, v[142:145] offset:9216
	s_mov_b32 s0, s9
	s_mov_b32 s9, s10
	s_mov_b32 s10, s11
	s_mov_b32 s11, s0
	v_mov_b32_e32 v32, v157
	v_add_u32_e32 v157, s10, v133
	v_add_u32_e32 v146, s11, v190
	s_add_i32 s4, s4, 1
	s_waitcnt lgkmcnt(0)
	s_barrier
	s_cmp_le_u32 s4, s5
	s_cbranch_scc1 .Lc_tile_loop
	v_mfma_f32_32x32x16_bf16 v[80:95], v[174:177], v[158:161], v[80:95]
	v_mfma_f32_32x32x16_bf16 v[16:31], v[182:185], v[158:161], v[16:31]
	v_mfma_f32_32x32x16_bf16 v[80:95], v[178:181], v[162:165], v[80:95]
	v_mfma_f32_32x32x16_bf16 v[16:31], v[186:189], v[162:165], v[16:31]
	s_cmp_gt_u32 s4, s8
	s_cbranch_scc1 .Lc_tiles_done
.Lc_idle_loop:
	global_load_dwordx4 v[204:207], v[138:139], off
	global_load_dwordx4 v[142:145], v[136:137], off
	v_lshl_add_u64 v[138:139], v[138:139], 0, s[2:3]
	v_lshl_add_u64 v[136:137], v[136:137], 0, s[18:19]
	s_waitcnt vmcnt(0)
	ds_write_b128 v146, v[204:207]
	ds_write_b128 v146, v[142:145] offset:9216
	s_mov_b32 s0, s9
	s_mov_b32 s9, s10
	s_mov_b32 s10, s11
	s_mov_b32 s11, s0
	v_add_u32_e32 v146, s11, v190
	s_add_i32 s4, s4, 1
	s_waitcnt lgkmcnt(0)
	s_barrier
	s_cmp_le_u32 s4, s8
	s_cbranch_scc1 .Lc_idle_loop
.Lc_tiles_done:
	v_add_f32_e32 v141, v141, v150
	v_add_f32_e32 v140, v140, v151
	s_mov_b64 s[0:1], exec
